# device-wide barrier rounds: the globally last XCD leader releases every XCC's waiting workgroups itself (eight release atomics)
# speedup vs baseline: 1.0020x; 1.0020x over previous
; __device__ __forceinline__ unsigned xb_ld(unsigned* p)              { return __hip_atomic_load(p, __ATOMIC_RELAXED, __HIP_MEMORY_SCOPE_AGENT); }
; __device__ __forceinline__ unsigned xb_add(unsigned* p, unsigned v) { return __hip_atomic_fetch_add(p, v, __ATOMIC_RELAXED, __HIP_MEMORY_SCOPE_AGENT); }
; #define XB_SPIN(cond, bar) do { unsigned _sp = 0; while (cond) { __builtin_amdgcn_s_sleep(1); \
;     if ((++_sp & 255u) == 0u) { if (xb_ld(&(bar)[XB_TMO])) break; if (_sp > XB_SPIN_CAP) { atomicAdd(&(bar)[XB_TMO], 1u); break; } } } } while (0)
; __device__ __forceinline__ void xcd_barrier(const XcdBarrier& b) {
;     ...
;             const unsigned og = xb_add(&bar[XB_TOP], 1u);
;             const unsigned tg = og / nx;
;             if (og + 1u == (tg + 1u) * nx) xb_add(&bar[XB_TOPGEN], 1u);
;             else XB_SPIN(xb_ld(&bar[XB_TOPGEN]) == tg, bar);
;             __builtin_amdgcn_fence(__ATOMIC_ACQUIRE, "agent");
;             xb_add(&bar[XB_XGEN(b.x)], 1u);
;             asm volatile("s_waitcnt vmcnt(0)" ::: "memory");
.Lglast_6:
	s_or_b64 exec, exec, s[6:7]
	v_readlane_b32 s10, v253, 40
	v_readlane_b32 s11, v253, 41
	s_nop 0
	s_sub_u32 s10, s10, 0x1100
	s_subb_u32 s11, s11, 0
	s_nop 1
	global_atomic_add v99, v195, s[10:11]
	global_atomic_add v99, v195, s[10:11] offset:256
	global_atomic_add v99, v195, s[10:11] offset:512
	global_atomic_add v99, v195, s[10:11] offset:768
	global_atomic_add v99, v195, s[10:11] offset:1024
	global_atomic_add v99, v195, s[10:11] offset:1280
	global_atomic_add v99, v195, s[10:11] offset:1536
	global_atomic_add v99, v195, s[10:11] offset:1792
	s_branch .LBB0_1263

; __device__ __forceinline__ unsigned xb_add(unsigned* p, unsigned v) { return __hip_atomic_fetch_add(p, v, __ATOMIC_RELAXED, __HIP_MEMORY_SCOPE_AGENT); }
; __device__ __forceinline__ void xcd_barrier(const XcdBarrier& b) {
;     ...
;             xb_add(&bar[XB_XGEN(b.x)], 1u);
.LBB0_1265:
	s_or_b64 exec, exec, s[6:7]
	s_mov_b64 s[6:7], exec
	v_mbcnt_lo_u32_b32 v1, s6, 0
	v_mbcnt_hi_u32_b32 v1, s7, v1
	v_cmp_eq_u32_e32 vcc, 0, v1
	s_and_saveexec_b64 s[8:9], vcc
	s_cbranch_execz .LBB0_1267
	s_bcnt1_i32_b64 s4, s[6:7]
	v_readlane_b32 s6, v253, 36
	v_mov_b32_e32 v1, s4
	v_readlane_b32 s7, v253, 37
	s_nop 4
	s_nop 0

; __device__ __forceinline__ unsigned xb_add(unsigned* p, unsigned v) { return __hip_atomic_fetch_add(p, v, __ATOMIC_RELAXED, __HIP_MEMORY_SCOPE_AGENT); }
; __device__ __forceinline__ void xcd_barrier(const XcdBarrier& b) {
;     ...
;             xb_add(&bar[XB_XGEN(b.x)], 1u);
.LBB0_1926:
	s_bcnt1_i32_b64 s4, s[6:7]
	v_readlane_b32 s6, v253, 36
	v_mov_b32_e32 v1, s4
	v_readlane_b32 s7, v253, 37
	s_nop 4
	s_nop 0
	s_getpc_b64 s[98:99]
